# attention: one static s_setprio 2 for blocks 256..511 (no per-segment toggles)
# speedup vs baseline: 1.0007x; 1.0007x over previous
.LBB0_313:
	s_andn2_b64 vcc, exec, s[0:1]
	s_cbranch_vccnz .LBB0_405
	s_bitcmp1_b32 s90, 8
	s_cbranch_scc0 .Lap_lo
	s_setprio 2
.Lap_lo:
	v_readlane_b32 s0, v255, 36
	v_readlane_b32 s1, v255, 37
	s_lshl_b32 s0, s0, 6
	s_ashr_i32 s1, s0, 31
	s_lshl_b64 s[0:1], s[0:1], 2
	v_readlane_b32 s2, v254, 49
	s_add_u32 s4, s2, s0
	v_readlane_b32 s0, v254, 50
	s_addc_u32 s5, s0, s1
	v_writelane_b32 v255, s4, 41
	v_mov_b32_e32 v0, v169
	s_nop 0
	v_writelane_b32 v255, s5, 42
	v_cmp_eq_u32_e64 s[0:1], 0, v0
	s_nop 1
	v_writelane_b32 v255, s0, 43
	s_nop 1
	v_writelane_b32 v255, s1, 44
	s_branch .LBB0_317

.LBB0_405:
	s_setprio 0
	s_mov_b64 s[0:1], 0
